# LDS-staged wide-store epilogues for hy_in fn_in fn_a gla_in; hyena conv loop LDS prefetch; on top of norm rewrite and GEMM K-step pipelining
# speedup vs baseline: 1.0161x; 1.0161x over previous
.LBB0_611:
	s_waitcnt lgkmcnt(0)
	s_barrier
	s_setprio 1
	ds_read_b128 v[200:203], v144 offset:36864
	ds_read_b128 v[204:207], v143 offset:55296
	ds_read_b128 v[208:211], v143 offset:59904
	ds_read_b128 v[212:215], v144 offset:41472
	ds_read_b128 v[232:235], v144 offset:36896
	ds_read_b128 v[236:239], v143 offset:55328
	ds_read_b128 v[240:243], v143 offset:59936
	ds_read_b128 v[244:247], v144 offset:41504
	s_waitcnt lgkmcnt(6)
	v_mfma_f32_32x32x16_bf16 v[48:63], v[200:203], v[204:207], v[48:63]
	s_waitcnt lgkmcnt(5)
	v_mfma_f32_32x32x16_bf16 v[32:47], v[200:203], v[208:211], v[32:47]
	ds_read_b128 v[200:203], v144 offset:36928
	s_waitcnt lgkmcnt(5)
	v_mfma_f32_32x32x16_bf16 v[16:31], v[212:215], v[204:207], v[16:31]
	ds_read_b128 v[204:207], v143 offset:55360
	v_mfma_f32_32x32x16_bf16 v[0:15], v[212:215], v[208:211], v[0:15]
	ds_read_b128 v[208:211], v143 offset:59968
	ds_read_b128 v[212:215], v144 offset:41536
	s_waitcnt lgkmcnt(6)
	v_mfma_f32_32x32x16_bf16 v[48:63], v[232:235], v[236:239], v[48:63]
	s_waitcnt lgkmcnt(5)
	v_mfma_f32_32x32x16_bf16 v[32:47], v[232:235], v[240:243], v[32:47]
	ds_read_b128 v[232:235], v144 offset:36960
	s_waitcnt lgkmcnt(5)
	v_mfma_f32_32x32x16_bf16 v[16:31], v[244:247], v[236:239], v[16:31]
	ds_read_b128 v[236:239], v143 offset:55392
	v_mfma_f32_32x32x16_bf16 v[0:15], v[244:247], v[240:243], v[0:15]
	ds_read_b128 v[240:243], v143 offset:60000
	ds_read_b128 v[244:247], v144 offset:41568
	s_waitcnt lgkmcnt(6)
	v_mfma_f32_32x32x16_bf16 v[48:63], v[200:203], v[204:207], v[48:63]
	s_waitcnt lgkmcnt(5)
	v_mfma_f32_32x32x16_bf16 v[32:47], v[200:203], v[208:211], v[32:47]
	s_waitcnt lgkmcnt(4)
	v_mfma_f32_32x32x16_bf16 v[16:31], v[212:215], v[204:207], v[16:31]
	v_mfma_f32_32x32x16_bf16 v[0:15], v[212:215], v[208:211], v[0:15]
	s_waitcnt lgkmcnt(2)
	v_mfma_f32_32x32x16_bf16 v[48:63], v[232:235], v[236:239], v[48:63]
	s_waitcnt lgkmcnt(1)
	v_mfma_f32_32x32x16_bf16 v[32:47], v[232:235], v[240:243], v[32:47]
	s_waitcnt lgkmcnt(0)
	v_mfma_f32_32x32x16_bf16 v[16:31], v[244:247], v[236:239], v[16:31]
	v_mfma_f32_32x32x16_bf16 v[0:15], v[244:247], v[240:243], v[0:15]
	s_setprio 0
	s_mul_i32 s5, s36, 0x6000
	s_mul_hi_i32 s4, s36, 0x6000
	s_add_u32 s5, s90, s5
	s_addc_u32 s4, s91, s4
	s_lshl_b64 s[2:3], s[2:3], 1
	s_add_u32 s2, s5, s2
	s_addc_u32 s3, s4, s3
	s_barrier
	v_and_b32_e32 v200, 63, v176
	v_lshrrev_b32_e32 v201, 6, v176
	v_mul_u32_u24_e32 v202, 0x2400, v201
	v_lshrrev_b32_e32 v203, 5, v200
	v_and_b32_e32 v204, 31, v200
	v_mul_u32_u24_e32 v203, 0x240, v203
	v_lshl_add_u32 v203, v204, 1, v203
	v_add_u32_e32 v203, v202, v203
	v_lshrrev_b32_e32 v204, 3, v200
	v_and_b32_e32 v205, 7, v200
	v_mul_u32_u24_e32 v206, 0x90, v204
	v_lshl_add_u32 v206, v205, 4, v206
	v_add_u32_e32 v206, v202, v206
	v_lshrrev_b32_e32 v207, 1, v201
	v_and_b32_e32 v208, 1, v201
	v_lshl_add_u32 v204, v207, 6, v204
	v_mul_u32_u24_e32 v204, 0x6000, v204
	v_lshl_add_u32 v204, v208, 7, v204
	v_lshl_add_u32 v204, v205, 4, v204
	v_cvt_pk_bf16_f32 v48, v48, v49
	v_cvt_pk_bf16_f32 v50, v50, v51
	v_cvt_pk_bf16_f32 v52, v52, v53
	v_cvt_pk_bf16_f32 v54, v54, v55
	v_cvt_pk_bf16_f32 v56, v56, v57
	v_cvt_pk_bf16_f32 v58, v58, v59
	v_cvt_pk_bf16_f32 v60, v60, v61
	v_cvt_pk_bf16_f32 v62, v62, v63
	ds_write_b16 v203, v48
	ds_write_b16_d16_hi v203, v48 offset:144
	ds_write_b16 v203, v50 offset:288
	ds_write_b16_d16_hi v203, v50 offset:432
	ds_write_b16 v203, v52 offset:1152
	ds_write_b16_d16_hi v203, v52 offset:1296
	ds_write_b16 v203, v54 offset:1440
	ds_write_b16_d16_hi v203, v54 offset:1584
	ds_write_b16 v203, v56 offset:2304
	ds_write_b16_d16_hi v203, v56 offset:2448
	ds_write_b16 v203, v58 offset:2592
	ds_write_b16_d16_hi v203, v58 offset:2736
	ds_write_b16 v203, v60 offset:3456
	ds_write_b16_d16_hi v203, v60 offset:3600
	ds_write_b16 v203, v62 offset:3744
	ds_write_b16_d16_hi v203, v62 offset:3888
	v_cvt_pk_bf16_f32 v32, v32, v33
	v_cvt_pk_bf16_f32 v34, v34, v35
	v_cvt_pk_bf16_f32 v36, v36, v37
	v_cvt_pk_bf16_f32 v38, v38, v39
	v_cvt_pk_bf16_f32 v40, v40, v41
	v_cvt_pk_bf16_f32 v42, v42, v43
	v_cvt_pk_bf16_f32 v44, v44, v45
	v_cvt_pk_bf16_f32 v46, v46, v47
	ds_write_b16 v203, v32 offset:64
	ds_write_b16_d16_hi v203, v32 offset:208
	ds_write_b16 v203, v34 offset:352
	ds_write_b16_d16_hi v203, v34 offset:496
	ds_write_b16 v203, v36 offset:1216
	ds_write_b16_d16_hi v203, v36 offset:1360
	ds_write_b16 v203, v38 offset:1504
	ds_write_b16_d16_hi v203, v38 offset:1648
	ds_write_b16 v203, v40 offset:2368
	ds_write_b16_d16_hi v203, v40 offset:2512
	ds_write_b16 v203, v42 offset:2656
	ds_write_b16_d16_hi v203, v42 offset:2800
	ds_write_b16 v203, v44 offset:3520
	ds_write_b16_d16_hi v203, v44 offset:3664
	ds_write_b16 v203, v46 offset:3808
	ds_write_b16_d16_hi v203, v46 offset:3952
	v_cvt_pk_bf16_f32 v16, v16, v17
	v_cvt_pk_bf16_f32 v18, v18, v19
	v_cvt_pk_bf16_f32 v20, v20, v21
	v_cvt_pk_bf16_f32 v22, v22, v23
	v_cvt_pk_bf16_f32 v24, v24, v25
	v_cvt_pk_bf16_f32 v26, v26, v27
	v_cvt_pk_bf16_f32 v28, v28, v29
	v_cvt_pk_bf16_f32 v30, v30, v31
	ds_write_b16 v203, v16 offset:4608
	ds_write_b16_d16_hi v203, v16 offset:4752
	ds_write_b16 v203, v18 offset:4896
	ds_write_b16_d16_hi v203, v18 offset:5040
	ds_write_b16 v203, v20 offset:5760
	ds_write_b16_d16_hi v203, v20 offset:5904
	ds_write_b16 v203, v22 offset:6048
	ds_write_b16_d16_hi v203, v22 offset:6192
	ds_write_b16 v203, v24 offset:6912
	ds_write_b16_d16_hi v203, v24 offset:7056
	ds_write_b16 v203, v26 offset:7200
	ds_write_b16_d16_hi v203, v26 offset:7344
	ds_write_b16 v203, v28 offset:8064
	ds_write_b16_d16_hi v203, v28 offset:8208
	ds_write_b16 v203, v30 offset:8352
	ds_write_b16_d16_hi v203, v30 offset:8496
	v_cvt_pk_bf16_f32 v0, v0, v1
	v_cvt_pk_bf16_f32 v2, v2, v3
	v_cvt_pk_bf16_f32 v4, v4, v5
	v_cvt_pk_bf16_f32 v6, v6, v7
	v_cvt_pk_bf16_f32 v8, v8, v9
	v_cvt_pk_bf16_f32 v10, v10, v11
	v_cvt_pk_bf16_f32 v12, v12, v13
	v_cvt_pk_bf16_f32 v14, v14, v15
	ds_write_b16 v203, v0 offset:4672
	ds_write_b16_d16_hi v203, v0 offset:4816
	ds_write_b16 v203, v2 offset:4960
	ds_write_b16_d16_hi v203, v2 offset:5104
	ds_write_b16 v203, v4 offset:5824
	ds_write_b16_d16_hi v203, v4 offset:5968
	ds_write_b16 v203, v6 offset:6112
	ds_write_b16_d16_hi v203, v6 offset:6256
	ds_write_b16 v203, v8 offset:6976
	ds_write_b16_d16_hi v203, v8 offset:7120
	ds_write_b16 v203, v10 offset:7264
	ds_write_b16_d16_hi v203, v10 offset:7408
	ds_write_b16 v203, v12 offset:8128
	ds_write_b16_d16_hi v203, v12 offset:8272
	ds_write_b16 v203, v14 offset:8416
	ds_write_b16_d16_hi v203, v14 offset:8560
	ds_read_b128 v[0:3], v206
	ds_read_b128 v[4:7], v206 offset:1152
	ds_read_b128 v[8:11], v206 offset:2304
	ds_read_b128 v[12:15], v206 offset:3456
	ds_read_b128 v[16:19], v206 offset:4608
	ds_read_b128 v[20:23], v206 offset:5760
	ds_read_b128 v[24:27], v206 offset:6912
	ds_read_b128 v[28:31], v206 offset:8064
	s_waitcnt lgkmcnt(7)
	global_store_dwordx4 v204, v[0:3], s[2:3]
	s_add_u32 s2, s2, 0x30000
	s_addc_u32 s3, s3, 0
	s_waitcnt lgkmcnt(6)
	global_store_dwordx4 v204, v[4:7], s[2:3]
	s_add_u32 s2, s2, 0x30000
	s_addc_u32 s3, s3, 0
	s_waitcnt lgkmcnt(5)
	global_store_dwordx4 v204, v[8:11], s[2:3]
	s_add_u32 s2, s2, 0x30000
	s_addc_u32 s3, s3, 0
	s_waitcnt lgkmcnt(4)
	global_store_dwordx4 v204, v[12:15], s[2:3]
	s_add_u32 s2, s2, 0x30000
	s_addc_u32 s3, s3, 0
	s_waitcnt lgkmcnt(3)
	global_store_dwordx4 v204, v[16:19], s[2:3]
	s_add_u32 s2, s2, 0x30000
	s_addc_u32 s3, s3, 0
	s_waitcnt lgkmcnt(2)
	global_store_dwordx4 v204, v[20:23], s[2:3]
	s_add_u32 s2, s2, 0x30000
	s_addc_u32 s3, s3, 0
	s_waitcnt lgkmcnt(1)
	global_store_dwordx4 v204, v[24:27], s[2:3]
	s_add_u32 s2, s2, 0x30000
	s_addc_u32 s3, s3, 0
	s_waitcnt lgkmcnt(0)
	global_store_dwordx4 v204, v[28:31], s[2:3]
	s_add_i32 s12, s12, s80
	s_mov_b64 s[10:11], -1
	s_andn2_b64 vcc, exec, s[0:1]
	s_mov_b32 s4, s20
	s_cbranch_vccz .LBB0_622

.LBB0_705:
	v_cmp_gt_u32_e32 vcc, s73, v32
	s_mov_b64 s[4:5], vcc
	s_nop 1
	v_cndmask_b32_e32 v220, 0, v33, vcc
	v_lshl_add_u32 v220, v220, 1, v121
	ds_read2_b32 v[36:37], v34 offset1:1
	ds_read2_b32 v[38:39], v34 offset0:2 offset1:3
	ds_read_b128 v[40:43], v220
	ds_read_b128 v[44:47], v220 offset:32
	ds_read2_b32 v[200:201], v34 offset0:8 offset1:9
	ds_read2_b32 v[202:203], v34 offset0:10 offset1:11
.Lconv_loop:
	v_add_u32_e32 v35, 1, v35
	v_add_u32_e32 v32, -1, v32
	v_cmp_gt_u32_e32 vcc, s73, v32
	v_subrev_u32_e32 v33, 40, v33
	v_subrev_u32_e32 v34, 64, v34
	s_mov_b64 s[6:7], vcc
	v_cndmask_b32_e32 v220, 0, v33, vcc
	v_lshl_add_u32 v220, v220, 1, v121
	ds_read2_b32 v[204:205], v34 offset1:1
	ds_read2_b32 v[206:207], v34 offset0:2 offset1:3
	ds_read_b128 v[208:211], v220
	ds_read_b128 v[212:215], v220 offset:32
	ds_read2_b32 v[216:217], v34 offset0:8 offset1:9
	ds_read2_b32 v[218:219], v34 offset0:10 offset1:11
	s_waitcnt lgkmcnt(6)
	v_cndmask_b32_e64 v40, 0, v40, s[4:5]
	v_cndmask_b32_e64 v41, 0, v41, s[4:5]
	v_cndmask_b32_e64 v42, 0, v42, s[4:5]
	v_cndmask_b32_e64 v43, 0, v43, s[4:5]
	v_cndmask_b32_e64 v44, 0, v44, s[4:5]
	v_cndmask_b32_e64 v45, 0, v45, s[4:5]
	v_cndmask_b32_e64 v46, 0, v46, s[4:5]
	v_cndmask_b32_e64 v47, 0, v47, s[4:5]
	s_nop 0
	v_mfma_f32_32x32x16_bf16 v[0:15], v[36:39], v[40:43], v[0:15]
	v_mfma_f32_32x32x16_bf16 v[0:15], v[200:203], v[44:47], v[0:15]
	v_cmp_ge_i32_e32 vcc, v35, v61
	s_or_b64 s[10:11], vcc, s[10:11]
	s_andn2_b64 exec, exec, s[10:11]
	s_cbranch_execz .Lconv_exit
	v_add_u32_e32 v35, 1, v35
	v_add_u32_e32 v32, -1, v32
	v_cmp_gt_u32_e32 vcc, s73, v32
	v_subrev_u32_e32 v33, 40, v33
	v_subrev_u32_e32 v34, 64, v34
	s_mov_b64 s[4:5], vcc
	v_cndmask_b32_e32 v220, 0, v33, vcc
	v_lshl_add_u32 v220, v220, 1, v121
	ds_read2_b32 v[36:37], v34 offset1:1
	ds_read2_b32 v[38:39], v34 offset0:2 offset1:3
	ds_read_b128 v[40:43], v220
	ds_read_b128 v[44:47], v220 offset:32
	ds_read2_b32 v[200:201], v34 offset0:8 offset1:9
	ds_read2_b32 v[202:203], v34 offset0:10 offset1:11
	s_waitcnt lgkmcnt(6)
	v_cndmask_b32_e64 v208, 0, v208, s[6:7]
	v_cndmask_b32_e64 v209, 0, v209, s[6:7]
	v_cndmask_b32_e64 v210, 0, v210, s[6:7]
	v_cndmask_b32_e64 v211, 0, v211, s[6:7]
	v_cndmask_b32_e64 v212, 0, v212, s[6:7]
	v_cndmask_b32_e64 v213, 0, v213, s[6:7]
	v_cndmask_b32_e64 v214, 0, v214, s[6:7]
	v_cndmask_b32_e64 v215, 0, v215, s[6:7]
	s_nop 0
	v_mfma_f32_32x32x16_bf16 v[0:15], v[204:207], v[208:211], v[0:15]
	v_mfma_f32_32x32x16_bf16 v[0:15], v[216:219], v[212:215], v[0:15]
	v_cmp_ge_i32_e32 vcc, v35, v61
	s_or_b64 s[10:11], vcc, s[10:11]
	s_andn2_b64 exec, exec, s[10:11]
	s_cbranch_execnz .Lconv_loop
.Lconv_exit:
	s_waitcnt lgkmcnt(0)
	s_or_b64 exec, exec, s[10:11]
	s_and_b64 s[4:5], s[8:9], exec
	s_cselect_b32 s4, s76, 0x9000
	v_lshl_add_u32 v32, v60, 1, s4
	ds_read2_b64 v[40:43], v32 offset1:2
	ds_read2_b64 v[32:35], v32 offset0:4 offset1:6
	ds_read2_b64 v[44:47], v55 offset1:2
	ds_read2_b64 v[36:39], v55 offset0:4 offset1:6
	s_waitcnt vmcnt(0)
	v_mov_b32_e32 v73, v72
	s_and_b64 vcc, exec, s[36:37]
	s_cbranch_vccz .LBB0_708
	ds_read2_b32 v[16:17], v123 offset0:112 offset1:113
	ds_read2_b32 v[18:19], v123 offset0:114 offset1:115
	ds_read_b128 v[20:23], v122 offset:2048
	ds_read_b128 v[48:51], v122 offset:2080
	ds_read2_b32 v[170:171], v123 offset0:120 offset1:121
	ds_read2_b32 v[172:173], v123 offset0:122 offset1:123
	s_waitcnt lgkmcnt(3)
	v_cndmask_b32_e64 v23, 0, v23, s[40:41]
	v_cndmask_b32_e64 v22, 0, v22, s[40:41]
	v_cndmask_b32_e64 v21, 0, v21, s[40:41]
	v_cndmask_b32_e64 v20, 0, v20, s[40:41]
	s_waitcnt lgkmcnt(2)
	v_cndmask_b32_e64 v51, 0, v51, s[40:41]
	v_cndmask_b32_e64 v50, 0, v50, s[40:41]
	v_mfma_f32_32x32x16_bf16 v[16:31], v[16:19], v[20:23], 0
	v_cndmask_b32_e64 v49, 0, v49, s[40:41]
	v_cndmask_b32_e64 v48, 0, v48, s[40:41]
	s_waitcnt lgkmcnt(0)
	s_nop 0
	v_mfma_f32_32x32x16_bf16 v[16:31], v[170:173], v[48:51], v[16:31]
	ds_read2_b32 v[48:49], v123 offset0:96 offset1:97
	ds_read2_b32 v[50:51], v123 offset0:98 offset1:99
	ds_read_b128 v[170:173], v124 offset:2048
	ds_read_b128 v[232:235], v124 offset:2080
	s_waitcnt lgkmcnt(1)
	v_cndmask_b32_e64 v173, 0, v173, s[42:43]
	v_cndmask_b32_e64 v172, 0, v172, s[42:43]
	v_cndmask_b32_e64 v171, 0, v171, s[42:43]
	v_cndmask_b32_e64 v170, 0, v170, s[42:43]
	s_nop 1
	v_mfma_f32_32x32x16_bf16 v[16:31], v[48:51], v[170:173], v[16:31]
	ds_read2_b32 v[48:49], v123 offset0:104 offset1:105
	ds_read2_b32 v[50:51], v123 offset0:106 offset1:107
	s_waitcnt lgkmcnt(2)
	v_cndmask_b32_e64 v173, 0, v235, s[42:43]
	v_cndmask_b32_e64 v172, 0, v234, s[42:43]
	v_cndmask_b32_e64 v171, 0, v233, s[42:43]
	v_cndmask_b32_e64 v170, 0, v232, s[42:43]
	s_waitcnt lgkmcnt(0)
	s_nop 0
	v_mfma_f32_32x32x16_bf16 v[16:31], v[48:51], v[170:173], v[16:31]
	ds_read2_b32 v[48:49], v123 offset0:80 offset1:81
	ds_read2_b32 v[50:51], v123 offset0:82 offset1:83
	ds_read_b128 v[170:173], v125 offset:2048
	ds_read_b128 v[232:235], v125 offset:2080
	s_waitcnt lgkmcnt(1)
	v_cndmask_b32_e64 v173, 0, v173, s[44:45]
	v_cndmask_b32_e64 v172, 0, v172, s[44:45]
	v_cndmask_b32_e64 v171, 0, v171, s[44:45]
	v_cndmask_b32_e64 v170, 0, v170, s[44:45]
	s_nop 1
	v_mfma_f32_32x32x16_bf16 v[16:31], v[48:51], v[170:173], v[16:31]
	ds_read2_b32 v[48:49], v123 offset0:88 offset1:89
	ds_read2_b32 v[50:51], v123 offset0:90 offset1:91
	s_waitcnt lgkmcnt(2)
	v_cndmask_b32_e64 v173, 0, v235, s[44:45]
	v_cndmask_b32_e64 v172, 0, v234, s[44:45]
	v_cndmask_b32_e64 v171, 0, v233, s[44:45]
	v_cndmask_b32_e64 v170, 0, v232, s[44:45]
	s_waitcnt lgkmcnt(0)
	s_nop 0
	v_mfma_f32_32x32x16_bf16 v[16:31], v[48:51], v[170:173], v[16:31]
	ds_read2_b32 v[48:49], v123 offset0:64 offset1:65
	ds_read2_b32 v[50:51], v123 offset0:66 offset1:67
	ds_read_b128 v[170:173], v126 offset:2048
	ds_read_b128 v[232:235], v126 offset:2080
	s_waitcnt lgkmcnt(1)
	v_cndmask_b32_e64 v173, 0, v173, s[46:47]
	v_cndmask_b32_e64 v172, 0, v172, s[46:47]
	v_cndmask_b32_e64 v171, 0, v171, s[46:47]
	v_cndmask_b32_e64 v170, 0, v170, s[46:47]
	s_nop 1
	v_mfma_f32_32x32x16_bf16 v[16:31], v[48:51], v[170:173], v[16:31]
	ds_read2_b32 v[48:49], v123 offset0:72 offset1:73
	ds_read2_b32 v[50:51], v123 offset0:74 offset1:75
	s_waitcnt lgkmcnt(2)
	v_cndmask_b32_e64 v173, 0, v235, s[46:47]
	v_cndmask_b32_e64 v172, 0, v234, s[46:47]
	v_cndmask_b32_e64 v171, 0, v233, s[46:47]
	v_cndmask_b32_e64 v170, 0, v232, s[46:47]
	s_waitcnt lgkmcnt(0)
	s_nop 0
	v_mfma_f32_32x32x16_bf16 v[16:31], v[48:51], v[170:173], v[16:31]
	ds_read2_b32 v[48:49], v123 offset0:48 offset1:49
	ds_read2_b32 v[50:51], v123 offset0:50 offset1:51
	ds_read_b128 v[170:173], v127 offset:2048
	ds_read_b128 v[232:235], v127 offset:2080
	s_waitcnt lgkmcnt(1)
	v_cndmask_b32_e64 v173, 0, v173, s[48:49]
	v_cndmask_b32_e64 v172, 0, v172, s[48:49]
	v_cndmask_b32_e64 v171, 0, v171, s[48:49]
	v_cndmask_b32_e64 v170, 0, v170, s[48:49]
	s_nop 1
	v_mfma_f32_32x32x16_bf16 v[16:31], v[48:51], v[170:173], v[16:31]
	ds_read2_b32 v[48:49], v123 offset0:56 offset1:57
	ds_read2_b32 v[50:51], v123 offset0:58 offset1:59
	s_waitcnt lgkmcnt(2)
	v_cndmask_b32_e64 v173, 0, v235, s[48:49]
	v_cndmask_b32_e64 v172, 0, v234, s[48:49]
	v_cndmask_b32_e64 v171, 0, v233, s[48:49]
	v_cndmask_b32_e64 v170, 0, v232, s[48:49]
	s_waitcnt lgkmcnt(0)
	s_nop 0
	v_mfma_f32_32x32x16_bf16 v[16:31], v[48:51], v[170:173], v[16:31]
	ds_read2_b32 v[48:49], v123 offset0:32 offset1:33
	ds_read2_b32 v[50:51], v123 offset0:34 offset1:35
	ds_read_b128 v[170:173], v128 offset:2048
	ds_read_b128 v[232:235], v128 offset:2080
	s_waitcnt lgkmcnt(1)
	v_cndmask_b32_e64 v173, 0, v173, s[50:51]
	v_cndmask_b32_e64 v172, 0, v172, s[50:51]
	v_cndmask_b32_e64 v171, 0, v171, s[50:51]
	v_cndmask_b32_e64 v170, 0, v170, s[50:51]
	s_nop 1
	v_mfma_f32_32x32x16_bf16 v[16:31], v[48:51], v[170:173], v[16:31]
	ds_read2_b32 v[48:49], v123 offset0:40 offset1:41
	ds_read2_b32 v[50:51], v123 offset0:42 offset1:43
	s_waitcnt lgkmcnt(2)
	v_cndmask_b32_e64 v173, 0, v235, s[50:51]
	v_cndmask_b32_e64 v172, 0, v234, s[50:51]
	v_cndmask_b32_e64 v171, 0, v233, s[50:51]
	v_cndmask_b32_e64 v170, 0, v232, s[50:51]
	s_waitcnt lgkmcnt(0)
	s_nop 0
	v_mfma_f32_32x32x16_bf16 v[16:31], v[48:51], v[170:173], v[16:31]
	ds_read2_b32 v[48:49], v123 offset0:16 offset1:17
	ds_read2_b32 v[50:51], v123 offset0:18 offset1:19
	ds_read_b128 v[170:173], v129 offset:2048
	ds_read_b128 v[232:235], v129 offset:2080
	s_waitcnt lgkmcnt(1)
	v_cndmask_b32_e64 v173, 0, v173, s[52:53]
	v_cndmask_b32_e64 v172, 0, v172, s[52:53]
	v_cndmask_b32_e64 v171, 0, v171, s[52:53]
	v_cndmask_b32_e64 v170, 0, v170, s[52:53]
	s_nop 1
	v_mfma_f32_32x32x16_bf16 v[16:31], v[48:51], v[170:173], v[16:31]
	ds_read2_b32 v[48:49], v123 offset0:24 offset1:25
	ds_read2_b32 v[50:51], v123 offset0:26 offset1:27
	s_waitcnt lgkmcnt(2)
	v_cndmask_b32_e64 v173, 0, v235, s[52:53]
	v_cndmask_b32_e64 v172, 0, v234, s[52:53]
	v_cndmask_b32_e64 v171, 0, v233, s[52:53]
	v_cndmask_b32_e64 v170, 0, v232, s[52:53]
	s_waitcnt lgkmcnt(0)
	s_nop 0
	v_mfma_f32_32x32x16_bf16 v[16:31], v[48:51], v[170:173], v[16:31]
	ds_read2_b32 v[48:49], v123 offset1:1
	ds_read2_b32 v[50:51], v123 offset0:2 offset1:3
	ds_read_b128 v[170:173], v130 offset:2048
	ds_read_b128 v[232:235], v130 offset:2080
	s_waitcnt lgkmcnt(1)
	v_cndmask_b32_e64 v173, 0, v173, s[54:55]
	v_cndmask_b32_e64 v172, 0, v172, s[54:55]
	v_cndmask_b32_e64 v171, 0, v171, s[54:55]
	v_cndmask_b32_e64 v170, 0, v170, s[54:55]
	s_nop 1
	v_mfma_f32_32x32x16_bf16 v[16:31], v[48:51], v[170:173], v[16:31]
	ds_read2_b32 v[48:49], v123 offset0:8 offset1:9
	ds_read2_b32 v[50:51], v123 offset0:10 offset1:11
	s_waitcnt lgkmcnt(2)
	v_cndmask_b32_e64 v173, 0, v235, s[54:55]
	v_cndmask_b32_e64 v172, 0, v234, s[54:55]
	v_cndmask_b32_e64 v171, 0, v233, s[54:55]
	v_cndmask_b32_e64 v170, 0, v232, s[54:55]
	s_waitcnt lgkmcnt(0)
	s_nop 0
	v_mfma_f32_32x32x16_bf16 v[16:31], v[48:51], v[170:173], v[16:31]
	ds_read2_b32 v[48:49], v132 offset1:1
	ds_read2_b32 v[50:51], v133 offset1:1
	ds_read_b128 v[170:173], v131 offset:2048
	ds_read_b128 v[232:235], v131 offset:2080
	s_waitcnt lgkmcnt(1)
	v_cndmask_b32_e64 v173, 0, v173, s[56:57]
	v_cndmask_b32_e64 v172, 0, v172, s[56:57]
	v_cndmask_b32_e64 v171, 0, v171, s[56:57]
	v_cndmask_b32_e64 v170, 0, v170, s[56:57]
	s_nop 1
	v_mfma_f32_32x32x16_bf16 v[16:31], v[48:51], v[170:173], v[16:31]
	ds_read2_b32 v[48:49], v134 offset1:1
	ds_read2_b32 v[50:51], v135 offset1:1
	s_waitcnt lgkmcnt(2)
	v_cndmask_b32_e64 v173, 0, v235, s[56:57]
	v_cndmask_b32_e64 v172, 0, v234, s[56:57]
	v_cndmask_b32_e64 v171, 0, v233, s[56:57]
	v_cndmask_b32_e64 v170, 0, v232, s[56:57]
	s_waitcnt lgkmcnt(0)
	s_nop 0
	v_mfma_f32_32x32x16_bf16 v[16:31], v[48:51], v[170:173], v[16:31]
	ds_read2_b32 v[48:49], v137 offset1:1
	ds_read2_b32 v[50:51], v138 offset1:1
	ds_read_b128 v[170:173], v136 offset:2048
	ds_read_b128 v[232:235], v136 offset:2080
	s_waitcnt lgkmcnt(1)
	v_cndmask_b32_e64 v173, 0, v173, s[58:59]
	v_cndmask_b32_e64 v172, 0, v172, s[58:59]
	v_cndmask_b32_e64 v171, 0, v171, s[58:59]
	v_cndmask_b32_e64 v170, 0, v170, s[58:59]
	s_nop 1
	v_mfma_f32_32x32x16_bf16 v[16:31], v[48:51], v[170:173], v[16:31]
	ds_read2_b32 v[48:49], v139 offset1:1
	ds_read2_b32 v[50:51], v140 offset1:1
	s_waitcnt lgkmcnt(2)
	v_cndmask_b32_e64 v173, 0, v235, s[58:59]
	v_cndmask_b32_e64 v172, 0, v234, s[58:59]
	v_cndmask_b32_e64 v171, 0, v233, s[58:59]
	v_cndmask_b32_e64 v170, 0, v232, s[58:59]
	s_waitcnt lgkmcnt(0)
	s_nop 0
	v_mfma_f32_32x32x16_bf16 v[16:31], v[48:51], v[170:173], v[16:31]
	ds_read2_b32 v[48:49], v142 offset1:1
	ds_read2_b32 v[50:51], v143 offset1:1
	ds_read_b128 v[170:173], v141 offset:2048
	ds_read_b128 v[232:235], v141 offset:2080
	s_waitcnt lgkmcnt(1)
	v_cndmask_b32_e64 v173, 0, v173, s[60:61]
	v_cndmask_b32_e64 v172, 0, v172, s[60:61]
	v_cndmask_b32_e64 v171, 0, v171, s[60:61]
	v_cndmask_b32_e64 v170, 0, v170, s[60:61]
	s_nop 1
	v_mfma_f32_32x32x16_bf16 v[16:31], v[48:51], v[170:173], v[16:31]
	ds_read2_b32 v[48:49], v144 offset1:1
	ds_read2_b32 v[50:51], v145 offset1:1
	s_waitcnt lgkmcnt(2)
	v_cndmask_b32_e64 v173, 0, v235, s[60:61]
	v_cndmask_b32_e64 v172, 0, v234, s[60:61]
	v_cndmask_b32_e64 v171, 0, v233, s[60:61]
	v_cndmask_b32_e64 v170, 0, v232, s[60:61]
	s_waitcnt lgkmcnt(0)
	s_nop 0
	v_mfma_f32_32x32x16_bf16 v[16:31], v[48:51], v[170:173], v[16:31]
	ds_read2_b32 v[48:49], v147 offset1:1
	ds_read2_b32 v[50:51], v148 offset1:1
	ds_read_b128 v[170:173], v146 offset:2048
	ds_read_b128 v[232:235], v146 offset:2080
	s_waitcnt lgkmcnt(1)
	v_cndmask_b32_e64 v173, 0, v173, s[62:63]
	v_cndmask_b32_e64 v172, 0, v172, s[62:63]
	v_cndmask_b32_e64 v171, 0, v171, s[62:63]
	v_cndmask_b32_e64 v170, 0, v170, s[62:63]
	s_nop 1
	v_mfma_f32_32x32x16_bf16 v[16:31], v[48:51], v[170:173], v[16:31]
	ds_read2_b32 v[48:49], v149 offset1:1
	ds_read2_b32 v[50:51], v150 offset1:1
	s_waitcnt lgkmcnt(2)
	v_cndmask_b32_e64 v173, 0, v235, s[62:63]
	v_cndmask_b32_e64 v172, 0, v234, s[62:63]
	v_cndmask_b32_e64 v171, 0, v233, s[62:63]
	v_cndmask_b32_e64 v170, 0, v232, s[62:63]
	s_waitcnt lgkmcnt(0)
	s_nop 0
	v_mfma_f32_32x32x16_bf16 v[16:31], v[48:51], v[170:173], v[16:31]
	ds_read2_b32 v[48:49], v152 offset1:1
	ds_read2_b32 v[50:51], v153 offset1:1
	ds_read_b128 v[170:173], v151 offset:2048
	ds_read_b128 v[232:235], v151 offset:2080
	s_waitcnt lgkmcnt(1)
	v_cndmask_b32_e64 v173, 0, v173, s[64:65]
	v_cndmask_b32_e64 v172, 0, v172, s[64:65]
	v_cndmask_b32_e64 v171, 0, v171, s[64:65]
	v_cndmask_b32_e64 v170, 0, v170, s[64:65]
	s_nop 1
	v_mfma_f32_32x32x16_bf16 v[16:31], v[48:51], v[170:173], v[16:31]
	ds_read2_b32 v[48:49], v154 offset1:1
	ds_read2_b32 v[50:51], v155 offset1:1
	s_waitcnt lgkmcnt(2)
	v_cndmask_b32_e64 v173, 0, v235, s[64:65]
	v_cndmask_b32_e64 v172, 0, v234, s[64:65]
	v_cndmask_b32_e64 v171, 0, v233, s[64:65]
	v_cndmask_b32_e64 v170, 0, v232, s[64:65]
	s_waitcnt lgkmcnt(0)
	s_nop 0
	v_mfma_f32_32x32x16_bf16 v[16:31], v[48:51], v[170:173], v[16:31]
	ds_read2_b32 v[48:49], v157 offset1:1
	ds_read2_b32 v[50:51], v158 offset1:1
	ds_read_b128 v[170:173], v156 offset:2048
	ds_read_b128 v[232:235], v156 offset:2080
	s_waitcnt lgkmcnt(1)
	v_cndmask_b32_e64 v173, 0, v173, s[66:67]
	v_cndmask_b32_e64 v172, 0, v172, s[66:67]
	v_cndmask_b32_e64 v171, 0, v171, s[66:67]
	v_cndmask_b32_e64 v170, 0, v170, s[66:67]
	s_nop 1
	v_mfma_f32_32x32x16_bf16 v[16:31], v[48:51], v[170:173], v[16:31]
	ds_read2_b32 v[48:49], v159 offset1:1
	ds_read2_b32 v[50:51], v160 offset1:1
	s_waitcnt lgkmcnt(2)
	v_cndmask_b32_e64 v173, 0, v235, s[66:67]
	v_cndmask_b32_e64 v172, 0, v234, s[66:67]
	v_cndmask_b32_e64 v171, 0, v233, s[66:67]
	v_cndmask_b32_e64 v170, 0, v232, s[66:67]
	s_waitcnt lgkmcnt(0)
	s_nop 0
	v_mfma_f32_32x32x16_bf16 v[16:31], v[48:51], v[170:173], v[16:31]
	ds_read2_b32 v[48:49], v162 offset1:1
	ds_read2_b32 v[50:51], v163 offset1:1
	ds_read_b128 v[170:173], v161 offset:2048
	ds_read_b128 v[232:235], v161 offset:2080
	s_waitcnt lgkmcnt(1)
	v_cndmask_b32_e64 v173, 0, v173, s[68:69]
	v_cndmask_b32_e64 v172, 0, v172, s[68:69]
	v_cndmask_b32_e64 v171, 0, v171, s[68:69]
	v_cndmask_b32_e64 v170, 0, v170, s[68:69]
	s_nop 1
	v_mfma_f32_32x32x16_bf16 v[16:31], v[48:51], v[170:173], v[16:31]
	ds_read2_b32 v[48:49], v164 offset1:1
	ds_read2_b32 v[50:51], v165 offset1:1
	s_waitcnt lgkmcnt(2)
	v_cndmask_b32_e64 v173, 0, v235, s[68:69]
	v_cndmask_b32_e64 v172, 0, v234, s[68:69]
	v_cndmask_b32_e64 v171, 0, v233, s[68:69]
	v_cndmask_b32_e64 v170, 0, v232, s[68:69]
	s_waitcnt lgkmcnt(0)
	s_nop 0
	v_mfma_f32_32x32x16_bf16 v[16:31], v[48:51], v[170:173], v[16:31]
	v_lshl_add_u32 v48, v54, 1, s4
	v_add_u32_e32 v48, 0x800, v48
	ds_read2_b64 v[170:173], v48 offset1:2
	ds_read2_b64 v[48:51], v48 offset0:4 offset1:6
	ds_read_b64 v[174:175], v84 offset:2048
	s_waitcnt lgkmcnt(2)
	v_lshlrev_b32_e32 v194, 16, v170
	v_and_b32_e32 v195, 0xffff0000, v170
	s_waitcnt lgkmcnt(0)
	v_lshlrev_b32_e32 v196, 16, v174
	v_and_b32_e32 v197, 0xffff0000, v174
	v_lshlrev_b32_e32 v174, 16, v175
	v_and_b32_e32 v175, 0xffff0000, v175
	v_lshlrev_b32_e32 v170, 16, v171
	v_and_b32_e32 v171, 0xffff0000, v171
	v_pk_fma_f32 v[18:19], v[72:73], v[174:175], v[18:19]
	v_pk_fma_f32 v[16:17], v[72:73], v[196:197], v[16:17]
	v_pk_mul_f32 v[18:19], v[18:19], v[170:171]
	ds_read_b64 v[170:171], v86 offset:2048
	v_pk_mul_f32 v[16:17], v[16:17], v[194:195]
	v_lshlrev_b32_e32 v174, 16, v172
	v_and_b32_e32 v175, 0xffff0000, v172
	v_lshlrev_b32_e32 v172, 16, v173
	s_waitcnt lgkmcnt(0)
	v_lshlrev_b32_e32 v194, 16, v170
	v_and_b32_e32 v195, 0xffff0000, v170
	v_lshlrev_b32_e32 v170, 16, v171
	v_and_b32_e32 v171, 0xffff0000, v171
	v_pk_fma_f32 v[22:23], v[72:73], v[170:171], v[22:23]
	ds_read_b64 v[170:171], v87 offset:2048
	v_pk_fma_f32 v[20:21], v[72:73], v[194:195], v[20:21]
	v_and_b32_e32 v173, 0xffff0000, v173
	v_pk_mul_f32 v[20:21], v[20:21], v[174:175]
	v_pk_mul_f32 v[22:23], v[22:23], v[172:173]
	s_waitcnt lgkmcnt(0)
	v_lshlrev_b32_e32 v174, 16, v170
	v_and_b32_e32 v175, 0xffff0000, v170
	v_lshlrev_b32_e32 v170, 16, v171
	v_and_b32_e32 v171, 0xffff0000, v171
	v_lshlrev_b32_e32 v172, 16, v48
	v_and_b32_e32 v173, 0xffff0000, v48
	v_lshlrev_b32_e32 v48, 16, v49
	v_and_b32_e32 v49, 0xffff0000, v49
	v_pk_fma_f32 v[26:27], v[72:73], v[170:171], v[26:27]
	v_pk_fma_f32 v[24:25], v[72:73], v[174:175], v[24:25]
	v_pk_mul_f32 v[26:27], v[26:27], v[48:49]
	ds_read_b64 v[48:49], v88 offset:2048
	v_pk_mul_f32 v[24:25], v[24:25], v[172:173]
	v_lshlrev_b32_e32 v170, 16, v50
	v_and_b32_e32 v171, 0xffff0000, v50
	v_lshlrev_b32_e32 v50, 16, v51
	s_waitcnt lgkmcnt(0)
	v_lshlrev_b32_e32 v172, 16, v48
	v_and_b32_e32 v173, 0xffff0000, v48
	v_lshlrev_b32_e32 v48, 16, v49
	v_and_b32_e32 v49, 0xffff0000, v49
	v_and_b32_e32 v51, 0xffff0000, v51
	v_pk_fma_f32 v[28:29], v[72:73], v[172:173], v[28:29]
	v_pk_fma_f32 v[30:31], v[72:73], v[48:49], v[30:31]
	v_pk_mul_f32 v[28:29], v[28:29], v[170:171]
	v_pk_mul_f32 v[30:31], v[30:31], v[50:51]

.LBB0_844:
	s_waitcnt lgkmcnt(0)
	s_barrier
	s_setprio 1
	ds_read_b128 v[200:203], v144 offset:36864
	ds_read_b128 v[204:207], v143 offset:55296
	ds_read_b128 v[208:211], v143 offset:59904
	ds_read_b128 v[212:215], v144 offset:41472
	ds_read_b128 v[232:235], v144 offset:36896
	ds_read_b128 v[236:239], v143 offset:55328
	ds_read_b128 v[240:243], v143 offset:59936
	ds_read_b128 v[244:247], v144 offset:41504
	s_waitcnt lgkmcnt(6)
	v_mfma_f32_32x32x16_bf16 v[48:63], v[200:203], v[204:207], v[48:63]
	s_waitcnt lgkmcnt(5)
	v_mfma_f32_32x32x16_bf16 v[32:47], v[200:203], v[208:211], v[32:47]
	ds_read_b128 v[200:203], v144 offset:36928
	s_waitcnt lgkmcnt(5)
	v_mfma_f32_32x32x16_bf16 v[16:31], v[212:215], v[204:207], v[16:31]
	ds_read_b128 v[204:207], v143 offset:55360
	v_mfma_f32_32x32x16_bf16 v[0:15], v[212:215], v[208:211], v[0:15]
	ds_read_b128 v[208:211], v143 offset:59968
	ds_read_b128 v[212:215], v144 offset:41536
	s_waitcnt lgkmcnt(6)
	v_mfma_f32_32x32x16_bf16 v[48:63], v[232:235], v[236:239], v[48:63]
	s_waitcnt lgkmcnt(5)
	v_mfma_f32_32x32x16_bf16 v[32:47], v[232:235], v[240:243], v[32:47]
	ds_read_b128 v[232:235], v144 offset:36960
	s_waitcnt lgkmcnt(5)
	v_mfma_f32_32x32x16_bf16 v[16:31], v[244:247], v[236:239], v[16:31]
	ds_read_b128 v[236:239], v143 offset:55392
	v_mfma_f32_32x32x16_bf16 v[0:15], v[244:247], v[240:243], v[0:15]
	ds_read_b128 v[240:243], v143 offset:60000
	ds_read_b128 v[244:247], v144 offset:41568
	s_waitcnt lgkmcnt(6)
	v_mfma_f32_32x32x16_bf16 v[48:63], v[200:203], v[204:207], v[48:63]
	s_waitcnt lgkmcnt(5)
	v_mfma_f32_32x32x16_bf16 v[32:47], v[200:203], v[208:211], v[32:47]
	s_waitcnt lgkmcnt(4)
	v_mfma_f32_32x32x16_bf16 v[16:31], v[212:215], v[204:207], v[16:31]
	v_mfma_f32_32x32x16_bf16 v[0:15], v[212:215], v[208:211], v[0:15]
	s_waitcnt lgkmcnt(2)
	v_mfma_f32_32x32x16_bf16 v[48:63], v[232:235], v[236:239], v[48:63]
	s_waitcnt lgkmcnt(1)
	v_mfma_f32_32x32x16_bf16 v[32:47], v[232:235], v[240:243], v[32:47]
	s_waitcnt lgkmcnt(0)
	v_mfma_f32_32x32x16_bf16 v[16:31], v[244:247], v[236:239], v[16:31]
	v_mfma_f32_32x32x16_bf16 v[0:15], v[244:247], v[240:243], v[0:15]
	s_setprio 0
	s_lshl_b64 s[4:5], s[36:37], 12
	s_add_u32 s4, s90, s4
	s_addc_u32 s5, s91, s5
	s_lshl_b64 s[2:3], s[2:3], 1
	s_add_u32 s2, s4, s2
	s_addc_u32 s3, s5, s3
	s_barrier
	v_and_b32_e32 v200, 63, v176
	v_lshrrev_b32_e32 v201, 6, v176
	v_mul_u32_u24_e32 v202, 0x2400, v201
	v_lshrrev_b32_e32 v203, 5, v200
	v_and_b32_e32 v204, 31, v200
	v_mul_u32_u24_e32 v203, 0x240, v203
	v_lshl_add_u32 v203, v204, 1, v203
	v_add_u32_e32 v203, v202, v203
	v_lshrrev_b32_e32 v204, 3, v200
	v_and_b32_e32 v205, 7, v200
	v_mul_u32_u24_e32 v206, 0x90, v204
	v_lshl_add_u32 v206, v205, 4, v206
	v_add_u32_e32 v206, v202, v206
	v_lshrrev_b32_e32 v207, 1, v201
	v_and_b32_e32 v208, 1, v201
	v_lshl_add_u32 v204, v207, 6, v204
	v_mul_u32_u24_e32 v204, 0x1000, v204
	v_lshl_add_u32 v204, v208, 7, v204
	v_lshl_add_u32 v204, v205, 4, v204
	v_cvt_pk_bf16_f32 v48, v48, v49
	v_cvt_pk_bf16_f32 v50, v50, v51
	v_cvt_pk_bf16_f32 v52, v52, v53
	v_cvt_pk_bf16_f32 v54, v54, v55
	v_cvt_pk_bf16_f32 v56, v56, v57
	v_cvt_pk_bf16_f32 v58, v58, v59
	v_cvt_pk_bf16_f32 v60, v60, v61
	v_cvt_pk_bf16_f32 v62, v62, v63
	ds_write_b16 v203, v48
	ds_write_b16_d16_hi v203, v48 offset:144
	ds_write_b16 v203, v50 offset:288
	ds_write_b16_d16_hi v203, v50 offset:432
	ds_write_b16 v203, v52 offset:1152
	ds_write_b16_d16_hi v203, v52 offset:1296
	ds_write_b16 v203, v54 offset:1440
	ds_write_b16_d16_hi v203, v54 offset:1584
	ds_write_b16 v203, v56 offset:2304
	ds_write_b16_d16_hi v203, v56 offset:2448
	ds_write_b16 v203, v58 offset:2592
	ds_write_b16_d16_hi v203, v58 offset:2736
	ds_write_b16 v203, v60 offset:3456
	ds_write_b16_d16_hi v203, v60 offset:3600
	ds_write_b16 v203, v62 offset:3744
	ds_write_b16_d16_hi v203, v62 offset:3888
	v_cvt_pk_bf16_f32 v32, v32, v33
	v_cvt_pk_bf16_f32 v34, v34, v35
	v_cvt_pk_bf16_f32 v36, v36, v37
	v_cvt_pk_bf16_f32 v38, v38, v39
	v_cvt_pk_bf16_f32 v40, v40, v41
	v_cvt_pk_bf16_f32 v42, v42, v43
	v_cvt_pk_bf16_f32 v44, v44, v45
	v_cvt_pk_bf16_f32 v46, v46, v47
	ds_write_b16 v203, v32 offset:64
	ds_write_b16_d16_hi v203, v32 offset:208
	ds_write_b16 v203, v34 offset:352
	ds_write_b16_d16_hi v203, v34 offset:496
	ds_write_b16 v203, v36 offset:1216
	ds_write_b16_d16_hi v203, v36 offset:1360
	ds_write_b16 v203, v38 offset:1504
	ds_write_b16_d16_hi v203, v38 offset:1648
	ds_write_b16 v203, v40 offset:2368
	ds_write_b16_d16_hi v203, v40 offset:2512
	ds_write_b16 v203, v42 offset:2656
	ds_write_b16_d16_hi v203, v42 offset:2800
	ds_write_b16 v203, v44 offset:3520
	ds_write_b16_d16_hi v203, v44 offset:3664
	ds_write_b16 v203, v46 offset:3808
	ds_write_b16_d16_hi v203, v46 offset:3952
	v_cvt_pk_bf16_f32 v16, v16, v17
	v_cvt_pk_bf16_f32 v18, v18, v19
	v_cvt_pk_bf16_f32 v20, v20, v21
	v_cvt_pk_bf16_f32 v22, v22, v23
	v_cvt_pk_bf16_f32 v24, v24, v25
	v_cvt_pk_bf16_f32 v26, v26, v27
	v_cvt_pk_bf16_f32 v28, v28, v29
	v_cvt_pk_bf16_f32 v30, v30, v31
	ds_write_b16 v203, v16 offset:4608
	ds_write_b16_d16_hi v203, v16 offset:4752
	ds_write_b16 v203, v18 offset:4896
	ds_write_b16_d16_hi v203, v18 offset:5040
	ds_write_b16 v203, v20 offset:5760
	ds_write_b16_d16_hi v203, v20 offset:5904
	ds_write_b16 v203, v22 offset:6048
	ds_write_b16_d16_hi v203, v22 offset:6192
	ds_write_b16 v203, v24 offset:6912
	ds_write_b16_d16_hi v203, v24 offset:7056
	ds_write_b16 v203, v26 offset:7200
	ds_write_b16_d16_hi v203, v26 offset:7344
	ds_write_b16 v203, v28 offset:8064
	ds_write_b16_d16_hi v203, v28 offset:8208
	ds_write_b16 v203, v30 offset:8352
	ds_write_b16_d16_hi v203, v30 offset:8496
	v_cvt_pk_bf16_f32 v0, v0, v1
	v_cvt_pk_bf16_f32 v2, v2, v3
	v_cvt_pk_bf16_f32 v4, v4, v5
	v_cvt_pk_bf16_f32 v6, v6, v7
	v_cvt_pk_bf16_f32 v8, v8, v9
	v_cvt_pk_bf16_f32 v10, v10, v11
	v_cvt_pk_bf16_f32 v12, v12, v13
	v_cvt_pk_bf16_f32 v14, v14, v15
	ds_write_b16 v203, v0 offset:4672
	ds_write_b16_d16_hi v203, v0 offset:4816
	ds_write_b16 v203, v2 offset:4960
	ds_write_b16_d16_hi v203, v2 offset:5104
	ds_write_b16 v203, v4 offset:5824
	ds_write_b16_d16_hi v203, v4 offset:5968
	ds_write_b16 v203, v6 offset:6112
	ds_write_b16_d16_hi v203, v6 offset:6256
	ds_write_b16 v203, v8 offset:6976
	ds_write_b16_d16_hi v203, v8 offset:7120
	ds_write_b16 v203, v10 offset:7264
	ds_write_b16_d16_hi v203, v10 offset:7408
	ds_write_b16 v203, v12 offset:8128
	ds_write_b16_d16_hi v203, v12 offset:8272
	ds_write_b16 v203, v14 offset:8416
	ds_write_b16_d16_hi v203, v14 offset:8560
	ds_read_b128 v[0:3], v206
	ds_read_b128 v[4:7], v206 offset:1152
	ds_read_b128 v[8:11], v206 offset:2304
	ds_read_b128 v[12:15], v206 offset:3456
	ds_read_b128 v[16:19], v206 offset:4608
	ds_read_b128 v[20:23], v206 offset:5760
	ds_read_b128 v[24:27], v206 offset:6912
	ds_read_b128 v[28:31], v206 offset:8064
	s_waitcnt lgkmcnt(7)
	global_store_dwordx4 v204, v[0:3], s[2:3]
	s_add_u32 s2, s2, 0x8000
	s_addc_u32 s3, s3, 0
	s_waitcnt lgkmcnt(6)
	global_store_dwordx4 v204, v[4:7], s[2:3]
	s_add_u32 s2, s2, 0x8000
	s_addc_u32 s3, s3, 0
	s_waitcnt lgkmcnt(5)
	global_store_dwordx4 v204, v[8:11], s[2:3]
	s_add_u32 s2, s2, 0x8000
	s_addc_u32 s3, s3, 0
	s_waitcnt lgkmcnt(4)
	global_store_dwordx4 v204, v[12:15], s[2:3]
	s_add_u32 s2, s2, 0x8000
	s_addc_u32 s3, s3, 0
	s_waitcnt lgkmcnt(3)
	global_store_dwordx4 v204, v[16:19], s[2:3]
	s_add_u32 s2, s2, 0x8000
	s_addc_u32 s3, s3, 0
	s_waitcnt lgkmcnt(2)
	global_store_dwordx4 v204, v[20:23], s[2:3]
	s_add_u32 s2, s2, 0x8000
	s_addc_u32 s3, s3, 0
	s_waitcnt lgkmcnt(1)
	global_store_dwordx4 v204, v[24:27], s[2:3]
	s_add_u32 s2, s2, 0x8000
	s_addc_u32 s3, s3, 0
	s_waitcnt lgkmcnt(0)
	global_store_dwordx4 v204, v[28:31], s[2:3]
	s_add_i32 s12, s12, s80
	s_mov_b64 s[10:11], -1
	s_andn2_b64 vcc, exec, s[0:1]
	s_mov_b32 s4, s20
	s_cbranch_vccz .LBB0_887

.LBB0_874:
	s_andn2_b64 vcc, exec, s[8:9]
	s_cbranch_vccnz .LBB0_859
	s_mul_i32 s5, s42, 0x1800
	s_mul_hi_i32 s4, s42, 0x1800
	s_add_u32 s6, s90, s5
	s_addc_u32 s7, s91, s4
	s_lshl_b64 s[4:5], s[40:41], 1
	s_add_u32 s4, s6, s4
	s_addc_u32 s5, s7, s5
	v_and_b32_e32 v200, 63, v176
	v_lshrrev_b32_e32 v201, 6, v176
	v_mul_u32_u24_e32 v202, 0x2400, v201
	v_lshrrev_b32_e32 v203, 5, v200
	v_and_b32_e32 v204, 31, v200
	v_mul_u32_u24_e32 v203, 0x240, v203
	v_lshl_add_u32 v203, v204, 1, v203
	v_add_u32_e32 v203, v202, v203
	v_lshrrev_b32_e32 v204, 3, v200
	v_and_b32_e32 v205, 7, v200
	v_mul_u32_u24_e32 v206, 0x90, v204
	v_lshl_add_u32 v206, v205, 4, v206
	v_add_u32_e32 v206, v202, v206
	v_lshrrev_b32_e32 v207, 1, v201
	v_and_b32_e32 v208, 1, v201
	v_lshl_add_u32 v204, v207, 6, v204
	v_mul_u32_u24_e32 v204, 0x1800, v204
	v_lshl_add_u32 v204, v208, 7, v204
	v_lshl_add_u32 v204, v205, 4, v204
	v_cvt_pk_bf16_f32 v48, v48, v49
	v_cvt_pk_bf16_f32 v50, v50, v51
	v_cvt_pk_bf16_f32 v52, v52, v53
	v_cvt_pk_bf16_f32 v54, v54, v55
	v_cvt_pk_bf16_f32 v56, v56, v57
	v_cvt_pk_bf16_f32 v58, v58, v59
	v_cvt_pk_bf16_f32 v60, v60, v61
	v_cvt_pk_bf16_f32 v62, v62, v63
	ds_write_b16 v203, v48
	ds_write_b16_d16_hi v203, v48 offset:144
	ds_write_b16 v203, v50 offset:288
	ds_write_b16_d16_hi v203, v50 offset:432
	ds_write_b16 v203, v52 offset:1152
	ds_write_b16_d16_hi v203, v52 offset:1296
	ds_write_b16 v203, v54 offset:1440
	ds_write_b16_d16_hi v203, v54 offset:1584
	ds_write_b16 v203, v56 offset:2304
	ds_write_b16_d16_hi v203, v56 offset:2448
	ds_write_b16 v203, v58 offset:2592
	ds_write_b16_d16_hi v203, v58 offset:2736
	ds_write_b16 v203, v60 offset:3456
	ds_write_b16_d16_hi v203, v60 offset:3600
	ds_write_b16 v203, v62 offset:3744
	ds_write_b16_d16_hi v203, v62 offset:3888
	v_cvt_pk_bf16_f32 v32, v32, v33
	v_cvt_pk_bf16_f32 v34, v34, v35
	v_cvt_pk_bf16_f32 v36, v36, v37
	v_cvt_pk_bf16_f32 v38, v38, v39
	v_cvt_pk_bf16_f32 v40, v40, v41
	v_cvt_pk_bf16_f32 v42, v42, v43
	v_cvt_pk_bf16_f32 v44, v44, v45
	v_cvt_pk_bf16_f32 v46, v46, v47
	ds_write_b16 v203, v32 offset:64
	ds_write_b16_d16_hi v203, v32 offset:208
	ds_write_b16 v203, v34 offset:352
	ds_write_b16_d16_hi v203, v34 offset:496
	ds_write_b16 v203, v36 offset:1216
	ds_write_b16_d16_hi v203, v36 offset:1360
	ds_write_b16 v203, v38 offset:1504
	ds_write_b16_d16_hi v203, v38 offset:1648
	ds_write_b16 v203, v40 offset:2368
	ds_write_b16_d16_hi v203, v40 offset:2512
	ds_write_b16 v203, v42 offset:2656
	ds_write_b16_d16_hi v203, v42 offset:2800
	ds_write_b16 v203, v44 offset:3520
	ds_write_b16_d16_hi v203, v44 offset:3664
	ds_write_b16 v203, v46 offset:3808
	ds_write_b16_d16_hi v203, v46 offset:3952
	v_cvt_pk_bf16_f32 v16, v16, v17
	v_cvt_pk_bf16_f32 v18, v18, v19
	v_cvt_pk_bf16_f32 v20, v20, v21
	v_cvt_pk_bf16_f32 v22, v22, v23
	v_cvt_pk_bf16_f32 v24, v24, v25
	v_cvt_pk_bf16_f32 v26, v26, v27
	v_cvt_pk_bf16_f32 v28, v28, v29
	v_cvt_pk_bf16_f32 v30, v30, v31
	ds_write_b16 v203, v16 offset:4608
	ds_write_b16_d16_hi v203, v16 offset:4752
	ds_write_b16 v203, v18 offset:4896
	ds_write_b16_d16_hi v203, v18 offset:5040
	ds_write_b16 v203, v20 offset:5760
	ds_write_b16_d16_hi v203, v20 offset:5904
	ds_write_b16 v203, v22 offset:6048
	ds_write_b16_d16_hi v203, v22 offset:6192
	ds_write_b16 v203, v24 offset:6912
	ds_write_b16_d16_hi v203, v24 offset:7056
	ds_write_b16 v203, v26 offset:7200
	ds_write_b16_d16_hi v203, v26 offset:7344
	ds_write_b16 v203, v28 offset:8064
	ds_write_b16_d16_hi v203, v28 offset:8208
	ds_write_b16 v203, v30 offset:8352
	ds_write_b16_d16_hi v203, v30 offset:8496
	v_cvt_pk_bf16_f32 v0, v0, v1
	v_cvt_pk_bf16_f32 v2, v2, v3
	v_cvt_pk_bf16_f32 v4, v4, v5
	v_cvt_pk_bf16_f32 v6, v6, v7
	v_cvt_pk_bf16_f32 v8, v8, v9
	v_cvt_pk_bf16_f32 v10, v10, v11
	v_cvt_pk_bf16_f32 v12, v12, v13
	v_cvt_pk_bf16_f32 v14, v14, v15
	ds_write_b16 v203, v0 offset:4672
	ds_write_b16_d16_hi v203, v0 offset:4816
	ds_write_b16 v203, v2 offset:4960
	ds_write_b16_d16_hi v203, v2 offset:5104
	ds_write_b16 v203, v4 offset:5824
	ds_write_b16_d16_hi v203, v4 offset:5968
	ds_write_b16 v203, v6 offset:6112
	ds_write_b16_d16_hi v203, v6 offset:6256
	ds_write_b16 v203, v8 offset:6976
	ds_write_b16_d16_hi v203, v8 offset:7120
	ds_write_b16 v203, v10 offset:7264
	ds_write_b16_d16_hi v203, v10 offset:7408
	ds_write_b16 v203, v12 offset:8128
	ds_write_b16_d16_hi v203, v12 offset:8272
	ds_write_b16 v203, v14 offset:8416
	ds_write_b16_d16_hi v203, v14 offset:8560
	ds_read_b128 v[0:3], v206
	ds_read_b128 v[4:7], v206 offset:1152
	ds_read_b128 v[8:11], v206 offset:2304
	ds_read_b128 v[12:15], v206 offset:3456
	ds_read_b128 v[16:19], v206 offset:4608
	ds_read_b128 v[20:23], v206 offset:5760
	ds_read_b128 v[24:27], v206 offset:6912
	ds_read_b128 v[28:31], v206 offset:8064
	s_waitcnt lgkmcnt(7)
	global_store_dwordx4 v204, v[0:3], s[4:5]
	s_add_u32 s4, s4, 0xc000
	s_addc_u32 s5, s5, 0
	s_waitcnt lgkmcnt(6)
	global_store_dwordx4 v204, v[4:7], s[4:5]
	s_add_u32 s4, s4, 0xc000
	s_addc_u32 s5, s5, 0
	s_waitcnt lgkmcnt(5)
	global_store_dwordx4 v204, v[8:11], s[4:5]
	s_add_u32 s4, s4, 0xc000
	s_addc_u32 s5, s5, 0
	s_waitcnt lgkmcnt(4)
	global_store_dwordx4 v204, v[12:15], s[4:5]
	s_add_u32 s4, s4, 0xc000
	s_addc_u32 s5, s5, 0
	s_waitcnt lgkmcnt(3)
	global_store_dwordx4 v204, v[16:19], s[4:5]
	s_add_u32 s4, s4, 0xc000
	s_addc_u32 s5, s5, 0
	s_waitcnt lgkmcnt(2)
	global_store_dwordx4 v204, v[20:23], s[4:5]
	s_add_u32 s4, s4, 0xc000
	s_addc_u32 s5, s5, 0
	s_waitcnt lgkmcnt(1)
	global_store_dwordx4 v204, v[24:27], s[4:5]
	s_add_u32 s4, s4, 0xc000
	s_addc_u32 s5, s5, 0
	s_waitcnt lgkmcnt(0)
	global_store_dwordx4 v204, v[28:31], s[4:5]
	s_branch .LBB0_859

.LBB0_1363:
	s_and_b32 s0, s8, 0xffffff80
	s_ashr_i32 s1, s0, 31
	s_and_b32 s11, s9, 0x180
	s_lshl_b64 s[4:5], s[0:1], 12
	s_add_u32 s1, s90, s4
	s_addc_u32 s5, s91, s5
	s_and_b32 s10, s3, 0x300
	s_lshl_b32 s4, s10, 1
	s_add_u32 s4, s1, s4
	s_addc_u32 s5, s5, 0
	s_lshl_b32 s76, s11, 9
	v_lshl_add_u64 v[118:119], v[136:137], 0, s[76:77]
	v_add_co_u32_e32 v122, vcc, s7, v118
	v_lshl_add_u64 v[0:1], s[4:5], 0, v[130:131]
	s_nop 0
	v_addc_co_u32_e32 v123, vcc, 0, v119, vcc
	v_add_co_u32_e32 v124, vcc, s13, v118
	v_lshl_add_u64 v[120:121], v[0:1], 0, v[64:65]
	s_nop 0
	v_addc_co_u32_e32 v125, vcc, 0, v119, vcc
	v_add_co_u32_e32 v126, vcc, s14, v118
	global_load_dwordx4 v[0:3], v[118:119], off
	global_load_dwordx4 v[4:7], v[122:123], off
	v_addc_co_u32_e32 v127, vcc, 0, v119, vcc
	global_load_dwordx4 v[8:11], v[124:125], off
	global_load_dwordx4 v[12:15], v[126:127], off
	global_load_dwordx4 v[16:19], v[120:121], off
	v_add_co_u32_e32 v128, vcc, s15, v120
	s_nop 1
	v_addc_co_u32_e32 v129, vcc, 0, v121, vcc
	v_add_co_u32_e32 v140, vcc, s16, v120
	global_load_dwordx4 v[20:23], v[128:129], off
	s_nop 0
	v_addc_co_u32_e32 v141, vcc, 0, v121, vcc
	global_load_dwordx4 v[24:27], v[140:141], off
	v_add_co_u32_e32 v142, vcc, s17, v120
	s_nop 1
	v_addc_co_u32_e32 v143, vcc, 0, v121, vcc
	global_load_dwordx4 v[28:31], v[142:143], off
	global_load_dwordx4 v[98:101], v[118:119], off offset:128
	global_load_dwordx4 v[102:105], v[122:123], off offset:128
	global_load_dwordx4 v[106:109], v[124:125], off offset:128
	global_load_dwordx4 v[110:113], v[126:127], off offset:128
	global_load_dwordx4 v[114:117], v[120:121], off offset:128
	global_load_dwordx4 v[152:155], v[128:129], off offset:128
	global_load_dwordx4 v[156:159], v[140:141], off offset:128
	global_load_dwordx4 v[160:163], v[142:143], off offset:128
	s_waitcnt vmcnt(63) expcnt(7) lgkmcnt(15)
	s_barrier
	s_waitcnt vmcnt(15)
	ds_write_b128 v132, v[0:3]
	s_waitcnt vmcnt(14)
	ds_write_b128 v132, v[4:7] offset:4608
	s_waitcnt vmcnt(13)
	ds_write_b128 v132, v[8:11] offset:9216
	s_waitcnt vmcnt(12)
	ds_write_b128 v132, v[12:15] offset:13824
	s_waitcnt vmcnt(11)
	ds_write_b128 v132, v[16:19] offset:18432
	s_waitcnt vmcnt(10)
	ds_write_b128 v132, v[20:23] offset:23040
	s_waitcnt vmcnt(9)
	ds_write_b128 v132, v[24:27] offset:27648
	s_waitcnt vmcnt(8)
	ds_write_b128 v132, v[28:31] offset:32256
	global_load_dwordx4 v[66:69], v[118:119], off offset:256
	global_load_dwordx4 v[70:73], v[122:123], off offset:256
	global_load_dwordx4 v[74:77], v[124:125], off offset:256
	global_load_dwordx4 v[78:81], v[126:127], off offset:256
	global_load_dwordx4 v[82:85], v[120:121], off offset:256
	global_load_dwordx4 v[86:89], v[128:129], off offset:256
	global_load_dwordx4 v[90:93], v[140:141], off offset:256
	global_load_dwordx4 v[94:97], v[142:143], off offset:256
	s_waitcnt lgkmcnt(0)
	s_barrier
	s_setprio 1
	ds_read_b128 v[200:203], v134
	ds_read_b128 v[204:207], v133 offset:18432
	ds_read_b128 v[208:211], v133 offset:23040
	ds_read_b128 v[212:215], v134 offset:32
	ds_read_b128 v[232:235], v133 offset:18464
	ds_read_b128 v[236:239], v133 offset:23072
	ds_read_b128 v[240:243], v134 offset:4608
	ds_read_b128 v[244:247], v134 offset:4640
	s_waitcnt lgkmcnt(6)
	v_mfma_f32_32x32x16_bf16 v[48:63], v[200:203], v[204:207], 0
	s_waitcnt lgkmcnt(5)
	v_mfma_f32_32x32x16_bf16 v[32:47], v[200:203], v[208:211], 0
	s_waitcnt vmcnt(15)
	ds_write_b128 v132, v[98:101] offset:36864
	ds_read_b128 v[200:203], v134 offset:64
	s_waitcnt lgkmcnt(5)
	v_mfma_f32_32x32x16_bf16 v[48:63], v[212:215], v[232:235], v[48:63]
	s_waitcnt vmcnt(14)
	ds_write_b128 v132, v[102:105] offset:41472
	s_waitcnt lgkmcnt(5)
	v_mfma_f32_32x32x16_bf16 v[32:47], v[212:215], v[236:239], v[32:47]
	s_waitcnt vmcnt(13)
	ds_write_b128 v132, v[106:109] offset:46080
	ds_read_b128 v[212:215], v133 offset:18496
	s_waitcnt lgkmcnt(6)
	v_mfma_f32_32x32x16_bf16 v[16:31], v[240:243], v[204:207], 0
	s_waitcnt vmcnt(12)
	ds_write_b128 v132, v[110:113] offset:50688
	ds_read_b128 v[204:207], v133 offset:23104
	v_mfma_f32_32x32x16_bf16 v[0:15], v[240:243], v[208:211], 0
	s_waitcnt vmcnt(11)
	ds_write_b128 v132, v[114:117] offset:55296
	ds_read_b128 v[208:211], v134 offset:4672
	ds_read_b128 v[240:243], v134 offset:96
	s_waitcnt lgkmcnt(10)
	v_mfma_f32_32x32x16_bf16 v[16:31], v[244:247], v[232:235], v[16:31]
	s_waitcnt vmcnt(10)
	ds_write_b128 v132, v[152:155] offset:59904
	ds_read_b128 v[232:235], v133 offset:18528
	v_mfma_f32_32x32x16_bf16 v[0:15], v[244:247], v[236:239], v[0:15]
	s_waitcnt vmcnt(9)
	ds_write_b128 v132, v[156:159] offset:64512
	ds_read_b128 v[236:239], v133 offset:23136
	ds_read_b128 v[244:247], v134 offset:4704
	s_waitcnt lgkmcnt(10)
	v_mfma_f32_32x32x16_bf16 v[48:63], v[200:203], v[212:215], v[48:63]
	s_waitcnt lgkmcnt(8)
	v_mfma_f32_32x32x16_bf16 v[32:47], v[200:203], v[204:207], v[32:47]
	s_waitcnt vmcnt(8)
	ds_write_b128 v135, v[160:163] offset:32256
	s_waitcnt lgkmcnt(7)
	v_mfma_f32_32x32x16_bf16 v[16:31], v[208:211], v[212:215], v[16:31]
	global_load_dwordx4 v[98:101], v[118:119], off offset:384
	v_mfma_f32_32x32x16_bf16 v[0:15], v[208:211], v[204:207], v[0:15]
	global_load_dwordx4 v[102:105], v[122:123], off offset:384
	s_waitcnt lgkmcnt(4)
	v_mfma_f32_32x32x16_bf16 v[48:63], v[240:243], v[232:235], v[48:63]
	global_load_dwordx4 v[106:109], v[124:125], off offset:384
	s_waitcnt lgkmcnt(2)
	v_mfma_f32_32x32x16_bf16 v[32:47], v[240:243], v[236:239], v[32:47]
	global_load_dwordx4 v[110:113], v[126:127], off offset:384
	s_waitcnt lgkmcnt(1)
	v_mfma_f32_32x32x16_bf16 v[16:31], v[244:247], v[232:235], v[16:31]
	global_load_dwordx4 v[114:117], v[120:121], off offset:384
	v_mfma_f32_32x32x16_bf16 v[0:15], v[244:247], v[236:239], v[0:15]
	s_setprio 0
	s_nop 0
	global_load_dwordx4 v[118:121], v[128:129], off offset:384
	global_load_dwordx4 v[122:125], v[140:141], off offset:384
	s_nop 0
	global_load_dwordx4 v[126:129], v[142:143], off offset:384
	s_waitcnt lgkmcnt(0)
	s_barrier
	s_setprio 1
	ds_read_b128 v[200:203], v134 offset:36864
	ds_read_b128 v[204:207], v133 offset:55296
	ds_read_b128 v[208:211], v133 offset:59904
	ds_read_b128 v[212:215], v134 offset:41472
	ds_read_b128 v[232:235], v134 offset:36896
	ds_read_b128 v[236:239], v133 offset:55328
	ds_read_b128 v[240:243], v133 offset:59936
	ds_read_b128 v[244:247], v134 offset:41504
	s_waitcnt lgkmcnt(6)
	v_mfma_f32_32x32x16_bf16 v[48:63], v[200:203], v[204:207], v[48:63]
	s_waitcnt lgkmcnt(5)
	v_mfma_f32_32x32x16_bf16 v[32:47], v[200:203], v[208:211], v[32:47]
	s_waitcnt vmcnt(15)
	ds_write_b128 v132, v[66:69]
	ds_read_b128 v[200:203], v134 offset:36928
	s_waitcnt lgkmcnt(6)
	v_mfma_f32_32x32x16_bf16 v[16:31], v[212:215], v[204:207], v[16:31]
	s_waitcnt vmcnt(14)
	ds_write_b128 v132, v[70:73] offset:4608
	ds_read_b128 v[204:207], v133 offset:55360
	v_mfma_f32_32x32x16_bf16 v[0:15], v[212:215], v[208:211], v[0:15]
	ds_read_b128 v[208:211], v133 offset:59968
	ds_read_b128 v[212:215], v134 offset:41536
	s_waitcnt lgkmcnt(8)
	v_mfma_f32_32x32x16_bf16 v[48:63], v[232:235], v[236:239], v[48:63]
	s_waitcnt vmcnt(13)
	ds_write_b128 v132, v[74:77] offset:9216
	s_waitcnt lgkmcnt(8)
	v_mfma_f32_32x32x16_bf16 v[32:47], v[232:235], v[240:243], v[32:47]
	ds_read_b128 v[232:235], v134 offset:36960
	s_waitcnt lgkmcnt(8)
	v_mfma_f32_32x32x16_bf16 v[16:31], v[244:247], v[236:239], v[16:31]
	s_waitcnt vmcnt(12)
	ds_write_b128 v132, v[78:81] offset:13824
	ds_read_b128 v[236:239], v133 offset:55392
	v_mfma_f32_32x32x16_bf16 v[0:15], v[244:247], v[240:243], v[0:15]
	ds_read_b128 v[240:243], v133 offset:60000
	ds_read_b128 v[244:247], v134 offset:41568
	s_waitcnt lgkmcnt(8)
	v_mfma_f32_32x32x16_bf16 v[48:63], v[200:203], v[204:207], v[48:63]
	s_waitcnt vmcnt(11)
	ds_write_b128 v132, v[82:85] offset:18432
	s_waitcnt lgkmcnt(8)
	v_mfma_f32_32x32x16_bf16 v[32:47], v[200:203], v[208:211], v[32:47]
	s_waitcnt lgkmcnt(7)
	v_mfma_f32_32x32x16_bf16 v[16:31], v[212:215], v[204:207], v[16:31]
	s_waitcnt vmcnt(10)
	ds_write_b128 v132, v[86:89] offset:23040
	v_mfma_f32_32x32x16_bf16 v[0:15], v[212:215], v[208:211], v[0:15]
	s_waitcnt lgkmcnt(4)
	v_mfma_f32_32x32x16_bf16 v[48:63], v[232:235], v[236:239], v[48:63]
	s_waitcnt vmcnt(9)
	ds_write_b128 v132, v[90:93] offset:27648
	s_waitcnt lgkmcnt(4)
	v_mfma_f32_32x32x16_bf16 v[32:47], v[232:235], v[240:243], v[32:47]
	s_waitcnt lgkmcnt(3)
	v_mfma_f32_32x32x16_bf16 v[16:31], v[244:247], v[236:239], v[16:31]
	s_waitcnt vmcnt(8)
	ds_write_b128 v132, v[94:97] offset:32256
	v_mfma_f32_32x32x16_bf16 v[0:15], v[244:247], v[240:243], v[0:15]
	s_setprio 0
	s_waitcnt lgkmcnt(0)
	s_barrier
	s_setprio 1
	ds_read_b128 v[200:203], v134
	ds_read_b128 v[204:207], v133 offset:18432
	ds_read_b128 v[208:211], v133 offset:23040
	ds_read_b128 v[212:215], v134 offset:4608
	ds_read_b128 v[232:235], v134 offset:32
	ds_read_b128 v[236:239], v133 offset:18464
	ds_read_b128 v[240:243], v133 offset:23072
	ds_read_b128 v[244:247], v134 offset:4640
	s_waitcnt lgkmcnt(6)
	v_mfma_f32_32x32x16_bf16 v[48:63], v[200:203], v[204:207], v[48:63]
	s_waitcnt lgkmcnt(5)
	v_mfma_f32_32x32x16_bf16 v[32:47], v[200:203], v[208:211], v[32:47]
	s_waitcnt vmcnt(7)
	ds_write_b128 v132, v[98:101] offset:36864
	ds_read_b128 v[200:203], v134 offset:64
	s_waitcnt lgkmcnt(6)
	v_mfma_f32_32x32x16_bf16 v[16:31], v[212:215], v[204:207], v[16:31]
	s_waitcnt vmcnt(6)
	ds_write_b128 v132, v[102:105] offset:41472
	ds_read_b128 v[204:207], v133 offset:18496
	v_mfma_f32_32x32x16_bf16 v[0:15], v[212:215], v[208:211], v[0:15]
	ds_read_b128 v[208:211], v133 offset:23104
	ds_read_b128 v[212:215], v134 offset:4672
	s_waitcnt lgkmcnt(8)
	v_mfma_f32_32x32x16_bf16 v[48:63], v[232:235], v[236:239], v[48:63]
	s_waitcnt vmcnt(5)
	ds_write_b128 v132, v[106:109] offset:46080
	s_waitcnt lgkmcnt(8)
	v_mfma_f32_32x32x16_bf16 v[32:47], v[232:235], v[240:243], v[32:47]
	ds_read_b128 v[232:235], v134 offset:96
	s_waitcnt lgkmcnt(8)
	v_mfma_f32_32x32x16_bf16 v[16:31], v[244:247], v[236:239], v[16:31]
	s_waitcnt vmcnt(4)
	ds_write_b128 v132, v[110:113] offset:50688
	ds_read_b128 v[236:239], v133 offset:18528
	v_mfma_f32_32x32x16_bf16 v[0:15], v[244:247], v[240:243], v[0:15]
	ds_read_b128 v[240:243], v133 offset:23136
	ds_read_b128 v[244:247], v134 offset:4704
	s_waitcnt lgkmcnt(8)
	v_mfma_f32_32x32x16_bf16 v[48:63], v[200:203], v[204:207], v[48:63]
	s_waitcnt vmcnt(3)
	ds_write_b128 v132, v[114:117] offset:55296
	s_waitcnt lgkmcnt(8)
	v_mfma_f32_32x32x16_bf16 v[32:47], v[200:203], v[208:211], v[32:47]
	s_waitcnt lgkmcnt(7)
	v_mfma_f32_32x32x16_bf16 v[16:31], v[212:215], v[204:207], v[16:31]
	s_waitcnt vmcnt(2)
	ds_write_b128 v132, v[118:121] offset:59904
	v_mfma_f32_32x32x16_bf16 v[0:15], v[212:215], v[208:211], v[0:15]
	s_waitcnt lgkmcnt(4)
	v_mfma_f32_32x32x16_bf16 v[48:63], v[232:235], v[236:239], v[48:63]
	s_waitcnt vmcnt(1)
	ds_write_b128 v132, v[122:125] offset:64512
	s_waitcnt lgkmcnt(4)
	v_mfma_f32_32x32x16_bf16 v[32:47], v[232:235], v[240:243], v[32:47]
	s_waitcnt lgkmcnt(3)
	v_mfma_f32_32x32x16_bf16 v[16:31], v[244:247], v[236:239], v[16:31]
	s_waitcnt vmcnt(0)
	ds_write_b128 v135, v[126:129] offset:32256
	v_mfma_f32_32x32x16_bf16 v[0:15], v[244:247], v[240:243], v[0:15]
	s_setprio 0
	s_waitcnt lgkmcnt(0)
	s_barrier
	s_setprio 1
	ds_read_b128 v[200:203], v134 offset:36864
	ds_read_b128 v[204:207], v133 offset:55296
	ds_read_b128 v[208:211], v133 offset:59904
	ds_read_b128 v[212:215], v134 offset:41472
	ds_read_b128 v[232:235], v134 offset:36896
	ds_read_b128 v[236:239], v133 offset:55328
	ds_read_b128 v[240:243], v133 offset:59936
	ds_read_b128 v[244:247], v134 offset:41504
	s_waitcnt lgkmcnt(6)
	v_mfma_f32_32x32x16_bf16 v[48:63], v[200:203], v[204:207], v[48:63]
	s_waitcnt lgkmcnt(5)
	v_mfma_f32_32x32x16_bf16 v[32:47], v[200:203], v[208:211], v[32:47]
	ds_read_b128 v[200:203], v134 offset:36928
	s_waitcnt lgkmcnt(5)
	v_mfma_f32_32x32x16_bf16 v[16:31], v[212:215], v[204:207], v[16:31]
	ds_read_b128 v[204:207], v133 offset:55360
	v_mfma_f32_32x32x16_bf16 v[0:15], v[212:215], v[208:211], v[0:15]
	ds_read_b128 v[208:211], v133 offset:59968
	ds_read_b128 v[212:215], v134 offset:41536
	s_waitcnt lgkmcnt(6)
	v_mfma_f32_32x32x16_bf16 v[48:63], v[232:235], v[236:239], v[48:63]
	s_waitcnt lgkmcnt(5)
	v_mfma_f32_32x32x16_bf16 v[32:47], v[232:235], v[240:243], v[32:47]
	ds_read_b128 v[232:235], v134 offset:36960
	s_waitcnt lgkmcnt(5)
	v_mfma_f32_32x32x16_bf16 v[16:31], v[244:247], v[236:239], v[16:31]
	ds_read_b128 v[236:239], v133 offset:55392
	v_mfma_f32_32x32x16_bf16 v[0:15], v[244:247], v[240:243], v[0:15]
	ds_read_b128 v[240:243], v133 offset:60000
	ds_read_b128 v[244:247], v134 offset:41568
	s_waitcnt lgkmcnt(6)
	v_mfma_f32_32x32x16_bf16 v[48:63], v[200:203], v[204:207], v[48:63]
	s_waitcnt lgkmcnt(5)
	v_mfma_f32_32x32x16_bf16 v[32:47], v[200:203], v[208:211], v[32:47]
	s_waitcnt lgkmcnt(4)
	v_mfma_f32_32x32x16_bf16 v[16:31], v[212:215], v[204:207], v[16:31]
	v_mfma_f32_32x32x16_bf16 v[0:15], v[212:215], v[208:211], v[0:15]
	s_waitcnt lgkmcnt(2)
	v_mfma_f32_32x32x16_bf16 v[48:63], v[232:235], v[236:239], v[48:63]
	s_waitcnt lgkmcnt(1)
	v_mfma_f32_32x32x16_bf16 v[32:47], v[232:235], v[240:243], v[32:47]
	s_waitcnt lgkmcnt(0)
	v_mfma_f32_32x32x16_bf16 v[16:31], v[244:247], v[236:239], v[16:31]
	v_mfma_f32_32x32x16_bf16 v[0:15], v[244:247], v[240:243], v[0:15]
	s_setprio 0
	s_barrier
	s_add_i32 s4, s0, 0xffffe000
	s_lshr_b32 s4, s4, 11
	s_lshr_b32 s5, s0, 8
	s_mov_b32 s1, 0x5000000
	s_movk_i32 s19, 0x7ff
	s_cmpk_gt_i32 s0, 0x1fff
	s_cselect_b32 s4, s4, s5
	s_cselect_b32 s18, 11, 8
	s_cselect_b32 s1, s1, 0x3000000
	s_cselect_b32 s19, s19, 0xff
	s_and_b32 s5, s0, s19
	s_lshl_b32 s4, s4, 10
	s_add_i32 s4, s4, s10
	s_and_b32 s20, s11, 0x80
	s_add_i32 s4, s4, s20
	s_add_i32 s20, s18, 1
	s_lshl_b32 s4, s4, s20
	s_lshr_b32 s21, s11, 8
	s_lshl_b32 s21, s21, s18
	s_add_i32 s4, s4, s21
	s_add_i32 s4, s4, s5
	s_lshl_b32 s4, s4, 1
	s_add_u32 s0, s90, s1
	s_addc_u32 s1, s91, 0
	s_add_u32 s0, s0, s4
	s_addc_u32 s1, s1, 0
	s_lshl_b32 s5, 4, s18
	s_lshl_b32 s19, s5, 3
	v_and_b32_e32 v200, 63, v176
	v_lshrrev_b32_e32 v201, 6, v176
	v_mul_u32_u24_e32 v202, 0x2400, v201
	v_lshrrev_b32_e32 v203, 5, v200
	v_and_b32_e32 v204, 31, v200
	v_mul_u32_u24_e32 v203, 0x240, v203
	v_lshl_add_u32 v203, v204, 1, v203
	v_add_u32_e32 v203, v202, v203
	v_lshrrev_b32_e32 v204, 3, v200
	v_and_b32_e32 v205, 7, v200
	v_mul_u32_u24_e32 v206, 0x90, v204
	v_lshl_add_u32 v206, v205, 4, v206
	v_add_u32_e32 v206, v202, v206
	v_lshrrev_b32_e32 v207, 1, v201
	v_and_b32_e32 v208, 1, v201
	v_lshl_add_u32 v204, v207, 6, v204
	v_mul_u32_u24_e32 v204, s5, v204
	v_lshl_add_u32 v204, v208, 7, v204
	v_lshl_add_u32 v204, v205, 4, v204
	v_cvt_pk_bf16_f32 v48, v48, v49
	v_cvt_pk_bf16_f32 v50, v50, v51
	v_cvt_pk_bf16_f32 v52, v52, v53
	v_cvt_pk_bf16_f32 v54, v54, v55
	v_cvt_pk_bf16_f32 v56, v56, v57
	v_cvt_pk_bf16_f32 v58, v58, v59
	v_cvt_pk_bf16_f32 v60, v60, v61
	v_cvt_pk_bf16_f32 v62, v62, v63
	ds_write_b16 v203, v48
	ds_write_b16_d16_hi v203, v48 offset:144
	ds_write_b16 v203, v50 offset:288
	ds_write_b16_d16_hi v203, v50 offset:432
	ds_write_b16 v203, v52 offset:1152
	ds_write_b16_d16_hi v203, v52 offset:1296
	ds_write_b16 v203, v54 offset:1440
	ds_write_b16_d16_hi v203, v54 offset:1584
	ds_write_b16 v203, v56 offset:2304
	ds_write_b16_d16_hi v203, v56 offset:2448
	ds_write_b16 v203, v58 offset:2592
	ds_write_b16_d16_hi v203, v58 offset:2736
	ds_write_b16 v203, v60 offset:3456
	ds_write_b16_d16_hi v203, v60 offset:3600
	ds_write_b16 v203, v62 offset:3744
	ds_write_b16_d16_hi v203, v62 offset:3888
	v_cvt_pk_bf16_f32 v32, v32, v33
	v_cvt_pk_bf16_f32 v34, v34, v35
	v_cvt_pk_bf16_f32 v36, v36, v37
	v_cvt_pk_bf16_f32 v38, v38, v39
	v_cvt_pk_bf16_f32 v40, v40, v41
	v_cvt_pk_bf16_f32 v42, v42, v43
	v_cvt_pk_bf16_f32 v44, v44, v45
	v_cvt_pk_bf16_f32 v46, v46, v47
	ds_write_b16 v203, v32 offset:64
	ds_write_b16_d16_hi v203, v32 offset:208
	ds_write_b16 v203, v34 offset:352
	ds_write_b16_d16_hi v203, v34 offset:496
	ds_write_b16 v203, v36 offset:1216
	ds_write_b16_d16_hi v203, v36 offset:1360
	ds_write_b16 v203, v38 offset:1504
	ds_write_b16_d16_hi v203, v38 offset:1648
	ds_write_b16 v203, v40 offset:2368
	ds_write_b16_d16_hi v203, v40 offset:2512
	ds_write_b16 v203, v42 offset:2656
	ds_write_b16_d16_hi v203, v42 offset:2800
	ds_write_b16 v203, v44 offset:3520
	ds_write_b16_d16_hi v203, v44 offset:3664
	ds_write_b16 v203, v46 offset:3808
	ds_write_b16_d16_hi v203, v46 offset:3952
	v_cvt_pk_bf16_f32 v16, v16, v17
	v_cvt_pk_bf16_f32 v18, v18, v19
	v_cvt_pk_bf16_f32 v20, v20, v21
	v_cvt_pk_bf16_f32 v22, v22, v23
	v_cvt_pk_bf16_f32 v24, v24, v25
	v_cvt_pk_bf16_f32 v26, v26, v27
	v_cvt_pk_bf16_f32 v28, v28, v29
	v_cvt_pk_bf16_f32 v30, v30, v31
	ds_write_b16 v203, v16 offset:4608
	ds_write_b16_d16_hi v203, v16 offset:4752
	ds_write_b16 v203, v18 offset:4896
	ds_write_b16_d16_hi v203, v18 offset:5040
	ds_write_b16 v203, v20 offset:5760
	ds_write_b16_d16_hi v203, v20 offset:5904
	ds_write_b16 v203, v22 offset:6048
	ds_write_b16_d16_hi v203, v22 offset:6192
	ds_write_b16 v203, v24 offset:6912
	ds_write_b16_d16_hi v203, v24 offset:7056
	ds_write_b16 v203, v26 offset:7200
	ds_write_b16_d16_hi v203, v26 offset:7344
	ds_write_b16 v203, v28 offset:8064
	ds_write_b16_d16_hi v203, v28 offset:8208
	ds_write_b16 v203, v30 offset:8352
	ds_write_b16_d16_hi v203, v30 offset:8496
	v_cvt_pk_bf16_f32 v0, v0, v1
	v_cvt_pk_bf16_f32 v2, v2, v3
	v_cvt_pk_bf16_f32 v4, v4, v5
	v_cvt_pk_bf16_f32 v6, v6, v7
	v_cvt_pk_bf16_f32 v8, v8, v9
	v_cvt_pk_bf16_f32 v10, v10, v11
	v_cvt_pk_bf16_f32 v12, v12, v13
	v_cvt_pk_bf16_f32 v14, v14, v15
	ds_write_b16 v203, v0 offset:4672
	ds_write_b16_d16_hi v203, v0 offset:4816
	ds_write_b16 v203, v2 offset:4960
	ds_write_b16_d16_hi v203, v2 offset:5104
	ds_write_b16 v203, v4 offset:5824
	ds_write_b16_d16_hi v203, v4 offset:5968
	ds_write_b16 v203, v6 offset:6112
	ds_write_b16_d16_hi v203, v6 offset:6256
	ds_write_b16 v203, v8 offset:6976
	ds_write_b16_d16_hi v203, v8 offset:7120
	ds_write_b16 v203, v10 offset:7264
	ds_write_b16_d16_hi v203, v10 offset:7408
	ds_write_b16 v203, v12 offset:8128
	ds_write_b16_d16_hi v203, v12 offset:8272
	ds_write_b16 v203, v14 offset:8416
	ds_write_b16_d16_hi v203, v14 offset:8560
	ds_read_b128 v[0:3], v206
	ds_read_b128 v[4:7], v206 offset:1152
	ds_read_b128 v[8:11], v206 offset:2304
	ds_read_b128 v[12:15], v206 offset:3456
	ds_read_b128 v[16:19], v206 offset:4608
	ds_read_b128 v[20:23], v206 offset:5760
	ds_read_b128 v[24:27], v206 offset:6912
	ds_read_b128 v[28:31], v206 offset:8064
	s_waitcnt lgkmcnt(7)
	global_store_dwordx4 v204, v[0:3], s[0:1]
	s_add_u32 s0, s0, s19
	s_addc_u32 s1, s1, 0
	s_waitcnt lgkmcnt(6)
	global_store_dwordx4 v204, v[4:7], s[0:1]
	s_add_u32 s0, s0, s19
	s_addc_u32 s1, s1, 0
	s_waitcnt lgkmcnt(5)
	global_store_dwordx4 v204, v[8:11], s[0:1]
	s_add_u32 s0, s0, s19
	s_addc_u32 s1, s1, 0
	s_waitcnt lgkmcnt(4)
	global_store_dwordx4 v204, v[12:15], s[0:1]
	s_add_u32 s0, s0, s19
	s_addc_u32 s1, s1, 0
	s_waitcnt lgkmcnt(3)
	global_store_dwordx4 v204, v[16:19], s[0:1]
	s_add_u32 s0, s0, s19
	s_addc_u32 s1, s1, 0
	s_waitcnt lgkmcnt(2)
	global_store_dwordx4 v204, v[20:23], s[0:1]
	s_add_u32 s0, s0, s19
	s_addc_u32 s1, s1, 0
	s_waitcnt lgkmcnt(1)
	global_store_dwordx4 v204, v[24:27], s[0:1]
	s_add_u32 s0, s0, s19
	s_addc_u32 s1, s1, 0
	s_waitcnt lgkmcnt(0)
	global_store_dwordx4 v204, v[28:31], s[0:1]
	s_add_i32 s2, s2, s6
	s_add_i32 s3, s3, s33
	s_add_i32 s8, s8, s12
	s_add_i32 s9, s9, s80
	s_cmpk_lt_i32 s2, 0x600
	s_cbranch_scc1 .LBB0_1363
	s_movk_i32 s76, 0x5000
